# grid barrier: non-leader workgroups issue their L1 invalidate before spinning on the generation word instead of after (no loads enter L1 while parked)
# speedup vs baseline: 1.0269x; 1.0113x over previous
; DI unsigned xb_ld(unsigned* p)              { return __hip_atomic_load(p, __ATOMIC_RELAXED, __HIP_MEMORY_SCOPE_AGENT); }
; DI unsigned xb_add(unsigned* p, unsigned v) { return __hip_atomic_fetch_add(p, v, __ATOMIC_RELAXED, __HIP_MEMORY_SCOPE_AGENT); }
; #define XB_SPIN(cond, bar) do { unsigned _sp = 0; while (cond) { __builtin_amdgcn_s_sleep(1); \
;     if ((++_sp & 255u) == 0u) { if (xb_ld(&(bar)[XB_TMO])) break; if (_sp > XB_SPIN_CAP) { atomicAdd(&(bar)[XB_TMO], 1u); break; } } } } while (0)
; DI void xcd_barrier(const XcdBarrier& b) {
;     ...
;         const unsigned old = xb_add(&bar[XB_XSUB(b.x)], 1u);
;         const unsigned gen = old / nloc;
;         if (old + 1u == (gen + 1u) * nloc) {
;             __builtin_amdgcn_fence(__ATOMIC_RELEASE, "agent");
;             asm volatile("s_waitcnt vmcnt(0)" ::: "memory");
;             const unsigned og = xb_add(&bar[XB_TOP], 1u);
;             const unsigned tg = og / nx;
;             if (og + 1u == (tg + 1u) * nx) xb_add(&bar[XB_TOPGEN], 1u);
;             else XB_SPIN(xb_ld(&bar[XB_TOPGEN]) == tg, bar);
;             __builtin_amdgcn_fence(__ATOMIC_ACQUIRE, "agent");
;             xb_add(&bar[XB_XGEN(b.x)], 1u);
;             asm volatile("s_waitcnt vmcnt(0)" ::: "memory");
;         } else {
;             XB_SPIN(xb_ld(&bar[XB_XGEN(b.x)]) == gen, bar);
.LBB0_141:
	s_or_b64 exec, exec, s[36:37]
	v_cvt_f32_u32_e32 v5, v3
	s_waitcnt vmcnt(0)
	v_readfirstlane_b32 s12, v4
	v_sub_u32_e32 v4, 0, v3
	v_rcp_iflag_f32_e32 v5, v5
	v_add_u32_e32 v6, s12, v0
	v_mul_f32_e32 v5, 0x4f7ffffe, v5
	v_cvt_u32_f32_e32 v5, v5
	v_mul_lo_u32 v0, v4, v5
	v_mul_hi_u32 v0, v5, v0
	v_add_u32_e32 v0, v5, v0
	v_mul_hi_u32 v0, v6, v0
	v_mul_lo_u32 v4, v0, v3
	v_sub_u32_e32 v4, v6, v4
	v_add_u32_e32 v5, 1, v0
	v_cmp_ge_u32_e32 vcc, v4, v3
	s_nop 1
	v_cndmask_b32_e32 v0, v0, v5, vcc
	v_sub_u32_e32 v5, v4, v3
	v_cndmask_b32_e32 v4, v4, v5, vcc
	v_add_u32_e32 v5, 1, v0
	v_cmp_ge_u32_e32 vcc, v4, v3
	v_add_u32_e32 v4, 1, v6
	s_nop 0
	v_cndmask_b32_e32 v0, v0, v5, vcc
	v_mul_lo_u32 v5, v3, v0
	v_add_u32_e32 v3, v5, v3
	v_cmp_ne_u32_e32 vcc, v4, v3
	s_and_saveexec_b64 s[12:13], vcc
	s_xor_b64 s[36:37], exec, s[12:13]
	s_cbranch_execz .LBB0_155
	v_readlane_b32 s12, v252, 10
	v_readlane_b32 s13, v252, 11
	s_waitcnt lgkmcnt(0)
	s_nop 3
	buffer_inv sc1
	global_load_dword v2, v1, s[12:13] sc1
	s_waitcnt vmcnt(0)
	v_cmp_eq_u32_e32 vcc, v2, v0
	s_and_saveexec_b64 s[38:39], vcc
	s_cbranch_execz .LBB0_154
	s_mov_b32 s12, 1
	s_mov_b64 s[40:41], 0
	s_branch .LBB0_145

; DI unsigned xb_ld(unsigned* p)              { return __hip_atomic_load(p, __ATOMIC_RELAXED, __HIP_MEMORY_SCOPE_AGENT); }
; #define XB_SPIN(cond, bar) do { unsigned _sp = 0; while (cond) { __builtin_amdgcn_s_sleep(1); \
;     if ((++_sp & 255u) == 0u) { if (xb_ld(&(bar)[XB_TMO])) break; if (_sp > XB_SPIN_CAP) { atomicAdd(&(bar)[XB_TMO], 1u); break; } } } } while (0)
; DI void xcd_barrier(const XcdBarrier& b) {
;     ...
;             XB_SPIN(xb_ld(&bar[XB_XGEN(b.x)]) == gen, bar);
;             __builtin_amdgcn_fence(__ATOMIC_ACQUIRE, "agent");
;             asm volatile("s_waitcnt vmcnt(0)" ::: "memory");
.LBB0_154:
	s_or_b64 exec, exec, s[38:39]
	s_waitcnt vmcnt(0)
	s_waitcnt vmcnt(0)
